# grid barrier: L1 invalidate (acquire) issued when a workgroup starts polling / together with the leader write-back instead of after the release is observed
# speedup vs baseline: 1.0063x; 1.0053x over previous
; __device__ __forceinline__ unsigned xb_ld(unsigned* p)              { return __hip_atomic_load(p, __ATOMIC_RELAXED, __HIP_MEMORY_SCOPE_AGENT); }
; __device__ __forceinline__ unsigned xb_add(unsigned* p, unsigned v) { return __hip_atomic_fetch_add(p, v, __ATOMIC_RELAXED, __HIP_MEMORY_SCOPE_AGENT); }
; #define XB_SPIN(cond, bar) do { unsigned _sp = 0; while (cond) { __builtin_amdgcn_s_sleep(1); \
;     if ((++_sp & 255u) == 0u) { if (xb_ld(&(bar)[XB_TMO])) break; if (_sp > XB_SPIN_CAP) { atomicAdd(&(bar)[XB_TMO], 1u); break; } } } } while (0)
; __device__ __forceinline__ void xcd_barrier(const XcdBarrier& b) {
;     ...
;         const unsigned old = xb_add(&bar[XB_XSUB(b.x)], 1u);
;         const unsigned gen = old / nloc;
;         if (old + 1u == (gen + 1u) * nloc) {
;             __builtin_amdgcn_fence(__ATOMIC_RELEASE, "agent");
;             asm volatile("s_waitcnt vmcnt(0)" ::: "memory");
;             const unsigned og = xb_add(&bar[XB_TOP], 1u);
;             const unsigned tg = og / nx;
;             if (og + 1u == (tg + 1u) * nx) xb_add(&bar[XB_TOPGEN], 1u);
;             else XB_SPIN(xb_ld(&bar[XB_TOPGEN]) == tg, bar);
;             __builtin_amdgcn_fence(__ATOMIC_ACQUIRE, "agent");
;             xb_add(&bar[XB_XGEN(b.x)], 1u);
;             asm volatile("s_waitcnt vmcnt(0)" ::: "memory");
;         } else {
;             XB_SPIN(xb_ld(&bar[XB_XGEN(b.x)]) == gen, bar);
.LBB0_130:
	s_or_b64 exec, exec, s[10:11]
	v_cvt_f32_u32_e32 v4, v2
	s_waitcnt vmcnt(0)
	v_readfirstlane_b32 s8, v3
	v_sub_u32_e32 v3, 0, v2
	v_rcp_iflag_f32_e32 v4, v4
	v_add_u32_e32 v5, s8, v1
	v_mul_f32_e32 v4, 0x4f7ffffe, v4
	v_cvt_u32_f32_e32 v4, v4
	v_mul_lo_u32 v1, v3, v4
	v_mul_hi_u32 v1, v4, v1
	v_add_u32_e32 v1, v4, v1
	v_mul_hi_u32 v1, v5, v1
	v_mul_lo_u32 v3, v1, v2
	v_sub_u32_e32 v3, v5, v3
	v_add_u32_e32 v4, 1, v1
	v_cmp_ge_u32_e32 vcc, v3, v2
	s_nop 1
	v_cndmask_b32_e32 v1, v1, v4, vcc
	v_sub_u32_e32 v4, v3, v2
	v_cndmask_b32_e32 v3, v3, v4, vcc
	v_add_u32_e32 v4, 1, v1
	v_cmp_ge_u32_e32 vcc, v3, v2
	v_add_u32_e32 v3, 1, v5
	s_nop 0
	v_cndmask_b32_e32 v1, v1, v4, vcc
	v_mul_lo_u32 v4, v2, v1
	v_add_u32_e32 v2, v4, v2
	v_cmp_ne_u32_e32 vcc, v3, v2
	s_and_saveexec_b64 s[8:9], vcc
	s_xor_b64 s[8:9], exec, s[8:9]
	s_cbranch_execz .LBB0_144
	buffer_inv sc1
	s_waitcnt lgkmcnt(0)
	v_mov_b32_e32 v0, 0x2000
	global_load_dword v0, v0, s[6:7] offset:1024 sc1
	s_add_u32 s16, s6, 0x2400
	s_addc_u32 s17, s7, 0
	s_waitcnt vmcnt(0)
	v_cmp_eq_u32_e32 vcc, v0, v1
	s_and_saveexec_b64 s[10:11], vcc
	s_cbranch_execz .LBB0_143
	s_add_u32 s14, s92, 0x3400200
	s_addc_u32 s15, s93, 0
	s_mov_b32 s28, 1
	s_mov_b64 s[18:19], 0
	v_mov_b32_e32 v0, 0
	s_branch .LBB0_134

; __device__ __forceinline__ unsigned xb_ld(unsigned* p)              { return __hip_atomic_load(p, __ATOMIC_RELAXED, __HIP_MEMORY_SCOPE_AGENT); }
; __device__ __forceinline__ unsigned xb_add(unsigned* p, unsigned v) { return __hip_atomic_fetch_add(p, v, __ATOMIC_RELAXED, __HIP_MEMORY_SCOPE_AGENT); }
; #define XB_SPIN(cond, bar) do { unsigned _sp = 0; while (cond) { __builtin_amdgcn_s_sleep(1); \
;     if ((++_sp & 255u) == 0u) { if (xb_ld(&(bar)[XB_TMO])) break; if (_sp > XB_SPIN_CAP) { atomicAdd(&(bar)[XB_TMO], 1u); break; } } } } while (0)
; __device__ __forceinline__ void xcd_barrier(const XcdBarrier& b) {
;     ...
;             __builtin_amdgcn_fence(__ATOMIC_RELEASE, "agent");
;             asm volatile("s_waitcnt vmcnt(0)" ::: "memory");
;             const unsigned og = xb_add(&bar[XB_TOP], 1u);
;             const unsigned tg = og / nx;
;             if (og + 1u == (tg + 1u) * nx) xb_add(&bar[XB_TOPGEN], 1u);
;             else XB_SPIN(xb_ld(&bar[XB_TOPGEN]) == tg, bar);
;             __builtin_amdgcn_fence(__ATOMIC_ACQUIRE, "agent");
;             xb_add(&bar[XB_XGEN(b.x)], 1u);
;             asm volatile("s_waitcnt vmcnt(0)" ::: "memory");
;         } else {
;             XB_SPIN(xb_ld(&bar[XB_XGEN(b.x)]) == gen, bar);
;             __builtin_amdgcn_fence(__ATOMIC_ACQUIRE, "agent");
;             asm volatile("s_waitcnt vmcnt(0)" ::: "memory");
.LBB0_143:
	s_or_b64 exec, exec, s[10:11]
	s_waitcnt vmcnt(0)
	s_waitcnt vmcnt(0)
.LBB0_144:
	s_andn2_saveexec_b64 s[8:9], s[8:9]
	s_cbranch_execz .LBB0_164
	s_mov_b64 s[8:9], exec
	buffer_wbl2 sc1
	buffer_inv sc1
	s_waitcnt lgkmcnt(0)
	s_waitcnt vmcnt(0)
	v_mbcnt_lo_u32_b32 v1, s8, 0
	v_mbcnt_hi_u32_b32 v1, s9, v1
	v_cmp_eq_u32_e32 vcc, 0, v1
	s_and_saveexec_b64 s[10:11], vcc
	s_cbranch_execz .LBB0_147
	s_bcnt1_i32_b64 s8, s[8:9]
	v_mov_b32_e32 v2, 0x3403000
	v_mov_b32_e32 v3, s8
	global_atomic_add v2, v2, v3, s[92:93] offset:1024 sc0

; __device__ __forceinline__ unsigned xb_ld(unsigned* p)              { return __hip_atomic_load(p, __ATOMIC_RELAXED, __HIP_MEMORY_SCOPE_AGENT); }
; __device__ __forceinline__ unsigned xb_add(unsigned* p, unsigned v) { return __hip_atomic_fetch_add(p, v, __ATOMIC_RELAXED, __HIP_MEMORY_SCOPE_AGENT); }
; #define XB_SPIN(cond, bar) do { unsigned _sp = 0; while (cond) { __builtin_amdgcn_s_sleep(1); \
;     if ((++_sp & 255u) == 0u) { if (xb_ld(&(bar)[XB_TMO])) break; if (_sp > XB_SPIN_CAP) { atomicAdd(&(bar)[XB_TMO], 1u); break; } } } } while (0)
; __device__ __forceinline__ void xcd_barrier(const XcdBarrier& b) {
;     ...
;             else XB_SPIN(xb_ld(&bar[XB_TOPGEN]) == tg, bar);
;             __builtin_amdgcn_fence(__ATOMIC_ACQUIRE, "agent");
;             xb_add(&bar[XB_XGEN(b.x)], 1u);
.LBB0_161:
	s_or_b64 exec, exec, s[8:9]
	s_mov_b64 s[8:9], exec
	v_mbcnt_lo_u32_b32 v0, s8, 0
	v_mbcnt_hi_u32_b32 v0, s9, v0
	v_cmp_eq_u32_e32 vcc, 0, v0
	s_waitcnt vmcnt(0)
	s_and_saveexec_b64 s[10:11], vcc
	s_cbranch_execz .LBB0_163
	s_bcnt1_i32_b64 s8, s[8:9]
	v_mov_b32_e32 v0, 0x2000
	v_mov_b32_e32 v1, s8
	global_atomic_add v0, v1, s[6:7] offset:1024

; __device__ __forceinline__ unsigned xb_ld(unsigned* p)              { return __hip_atomic_load(p, __ATOMIC_RELAXED, __HIP_MEMORY_SCOPE_AGENT); }
; __device__ __forceinline__ unsigned xb_add(unsigned* p, unsigned v) { return __hip_atomic_fetch_add(p, v, __ATOMIC_RELAXED, __HIP_MEMORY_SCOPE_AGENT); }
; #define XB_SPIN(cond, bar) do { unsigned _sp = 0; while (cond) { __builtin_amdgcn_s_sleep(1); \
;     if ((++_sp & 255u) == 0u) { if (xb_ld(&(bar)[XB_TMO])) break; if (_sp > XB_SPIN_CAP) { atomicAdd(&(bar)[XB_TMO], 1u); break; } } } } while (0)
; __device__ __forceinline__ void xcd_barrier(const XcdBarrier& b) {
;     ...
;         const unsigned old = xb_add(&bar[XB_XSUB(b.x)], 1u);
;         const unsigned gen = old / nloc;
;         if (old + 1u == (gen + 1u) * nloc) {
;             __builtin_amdgcn_fence(__ATOMIC_RELEASE, "agent");
;             asm volatile("s_waitcnt vmcnt(0)" ::: "memory");
;             const unsigned og = xb_add(&bar[XB_TOP], 1u);
;             const unsigned tg = og / nx;
;             if (og + 1u == (tg + 1u) * nx) xb_add(&bar[XB_TOPGEN], 1u);
;             else XB_SPIN(xb_ld(&bar[XB_TOPGEN]) == tg, bar);
;             __builtin_amdgcn_fence(__ATOMIC_ACQUIRE, "agent");
;             xb_add(&bar[XB_XGEN(b.x)], 1u);
;             asm volatile("s_waitcnt vmcnt(0)" ::: "memory");
;         } else {
;             XB_SPIN(xb_ld(&bar[XB_XGEN(b.x)]) == gen, bar);
.LBB0_201:
	s_or_b64 exec, exec, s[30:31]
	v_cvt_f32_u32_e32 v4, v2
	s_waitcnt vmcnt(0)
	v_readfirstlane_b32 s4, v3
	v_sub_u32_e32 v3, 0, v2
	v_rcp_iflag_f32_e32 v4, v4
	v_add_u32_e32 v5, s4, v1
	v_mul_f32_e32 v4, 0x4f7ffffe, v4
	v_cvt_u32_f32_e32 v4, v4
	v_mul_lo_u32 v1, v3, v4
	v_mul_hi_u32 v1, v4, v1
	v_add_u32_e32 v1, v4, v1
	v_mul_hi_u32 v1, v5, v1
	v_mul_lo_u32 v3, v1, v2
	v_sub_u32_e32 v3, v5, v3
	v_add_u32_e32 v4, 1, v1
	v_cmp_ge_u32_e32 vcc, v3, v2
	s_nop 1
	v_cndmask_b32_e32 v1, v1, v4, vcc
	v_sub_u32_e32 v4, v3, v2
	v_cndmask_b32_e32 v3, v3, v4, vcc
	v_add_u32_e32 v4, 1, v1
	v_cmp_ge_u32_e32 vcc, v3, v2
	v_add_u32_e32 v3, 1, v5
	s_nop 0
	v_cndmask_b32_e32 v1, v1, v4, vcc
	v_mul_lo_u32 v4, v2, v1
	v_add_u32_e32 v2, v4, v2
	v_cmp_ne_u32_e32 vcc, v3, v2
	s_and_saveexec_b64 s[4:5], vcc
	s_xor_b64 s[30:31], exec, s[4:5]
	s_cbranch_execz .LBB0_215
	buffer_inv sc1
	v_readlane_b32 s4, v255, 4
	s_waitcnt lgkmcnt(0)
	v_mov_b32_e32 v0, 0
	v_readlane_b32 s5, v255, 5
	s_nop 4
	global_load_dword v2, v0, s[4:5] sc1
	s_waitcnt vmcnt(0)
	v_cmp_eq_u32_e32 vcc, v2, v1
	s_and_saveexec_b64 s[34:35], vcc
	s_cbranch_execz .LBB0_214
	s_mov_b32 s4, 1
	s_mov_b64 s[36:37], 0
	s_branch .LBB0_205

; __device__ __forceinline__ unsigned xb_ld(unsigned* p)              { return __hip_atomic_load(p, __ATOMIC_RELAXED, __HIP_MEMORY_SCOPE_AGENT); }
; __device__ __forceinline__ unsigned xb_add(unsigned* p, unsigned v) { return __hip_atomic_fetch_add(p, v, __ATOMIC_RELAXED, __HIP_MEMORY_SCOPE_AGENT); }
; #define XB_SPIN(cond, bar) do { unsigned _sp = 0; while (cond) { __builtin_amdgcn_s_sleep(1); \
;     if ((++_sp & 255u) == 0u) { if (xb_ld(&(bar)[XB_TMO])) break; if (_sp > XB_SPIN_CAP) { atomicAdd(&(bar)[XB_TMO], 1u); break; } } } } while (0)
; __device__ __forceinline__ void xcd_barrier(const XcdBarrier& b) {
;     ...
;             __builtin_amdgcn_fence(__ATOMIC_RELEASE, "agent");
;             asm volatile("s_waitcnt vmcnt(0)" ::: "memory");
;             const unsigned og = xb_add(&bar[XB_TOP], 1u);
;             const unsigned tg = og / nx;
;             if (og + 1u == (tg + 1u) * nx) xb_add(&bar[XB_TOPGEN], 1u);
;             else XB_SPIN(xb_ld(&bar[XB_TOPGEN]) == tg, bar);
;             __builtin_amdgcn_fence(__ATOMIC_ACQUIRE, "agent");
;             xb_add(&bar[XB_XGEN(b.x)], 1u);
;             asm volatile("s_waitcnt vmcnt(0)" ::: "memory");
;         } else {
;             XB_SPIN(xb_ld(&bar[XB_XGEN(b.x)]) == gen, bar);
;             __builtin_amdgcn_fence(__ATOMIC_ACQUIRE, "agent");
;             asm volatile("s_waitcnt vmcnt(0)" ::: "memory");
.LBB0_214:
	s_or_b64 exec, exec, s[34:35]
	s_waitcnt vmcnt(0)
	s_waitcnt vmcnt(0)
.LBB0_215:
	s_andn2_saveexec_b64 s[4:5], s[30:31]
	s_cbranch_execz .LBB0_235
	s_mov_b64 s[30:31], exec
	buffer_wbl2 sc1
	buffer_inv sc1
	s_waitcnt lgkmcnt(0)
	s_waitcnt vmcnt(0)
	v_mbcnt_lo_u32_b32 v1, s30, 0
	v_mbcnt_hi_u32_b32 v1, s31, v1
	v_cmp_eq_u32_e32 vcc, 0, v1
	s_and_saveexec_b64 s[34:35], vcc
	s_cbranch_execz .LBB0_218
	s_bcnt1_i32_b64 s4, s[30:31]
	v_mov_b32_e32 v3, s4
	v_readlane_b32 s4, v255, 6
	v_mov_b32_e32 v2, 0
	v_readlane_b32 s5, v255, 7
	s_nop 4
	global_atomic_add v2, v2, v3, s[4:5] sc0

; __device__ __forceinline__ unsigned xb_ld(unsigned* p)              { return __hip_atomic_load(p, __ATOMIC_RELAXED, __HIP_MEMORY_SCOPE_AGENT); }
; __device__ __forceinline__ unsigned xb_add(unsigned* p, unsigned v) { return __hip_atomic_fetch_add(p, v, __ATOMIC_RELAXED, __HIP_MEMORY_SCOPE_AGENT); }
; #define XB_SPIN(cond, bar) do { unsigned _sp = 0; while (cond) { __builtin_amdgcn_s_sleep(1); \
;     if ((++_sp & 255u) == 0u) { if (xb_ld(&(bar)[XB_TMO])) break; if (_sp > XB_SPIN_CAP) { atomicAdd(&(bar)[XB_TMO], 1u); break; } } } } while (0)
; __device__ __forceinline__ void xcd_barrier(const XcdBarrier& b) {
;     ...
;             else XB_SPIN(xb_ld(&bar[XB_TOPGEN]) == tg, bar);
;             __builtin_amdgcn_fence(__ATOMIC_ACQUIRE, "agent");
;             xb_add(&bar[XB_XGEN(b.x)], 1u);
.LBB0_232:
	s_or_b64 exec, exec, s[30:31]
	s_mov_b64 s[30:31], exec
	v_mbcnt_lo_u32_b32 v0, s30, 0
	v_mbcnt_hi_u32_b32 v0, s31, v0
	v_cmp_eq_u32_e32 vcc, 0, v0
	s_waitcnt vmcnt(0)
	s_and_saveexec_b64 s[34:35], vcc
	s_cbranch_execz .LBB0_234
	s_bcnt1_i32_b64 s4, s[30:31]
	v_mov_b32_e32 v1, s4
	v_readlane_b32 s4, v255, 4
	v_mov_b32_e32 v0, 0
	v_readlane_b32 s5, v255, 5
	s_nop 4
	global_atomic_add v0, v1, s[4:5]

; __device__ __forceinline__ unsigned xb_ld(unsigned* p)              { return __hip_atomic_load(p, __ATOMIC_RELAXED, __HIP_MEMORY_SCOPE_AGENT); }
; __device__ __forceinline__ unsigned xb_add(unsigned* p, unsigned v) { return __hip_atomic_fetch_add(p, v, __ATOMIC_RELAXED, __HIP_MEMORY_SCOPE_AGENT); }
; #define XB_SPIN(cond, bar) do { unsigned _sp = 0; while (cond) { __builtin_amdgcn_s_sleep(1); \
;     if ((++_sp & 255u) == 0u) { if (xb_ld(&(bar)[XB_TMO])) break; if (_sp > XB_SPIN_CAP) { atomicAdd(&(bar)[XB_TMO], 1u); break; } } } } while (0)
; __device__ __forceinline__ void xcd_barrier(const XcdBarrier& b) {
;     ...
;         const unsigned old = xb_add(&bar[XB_XSUB(b.x)], 1u);
;         const unsigned gen = old / nloc;
;         if (old + 1u == (gen + 1u) * nloc) {
;             __builtin_amdgcn_fence(__ATOMIC_RELEASE, "agent");
;             asm volatile("s_waitcnt vmcnt(0)" ::: "memory");
;             const unsigned og = xb_add(&bar[XB_TOP], 1u);
;             const unsigned tg = og / nx;
;             if (og + 1u == (tg + 1u) * nx) xb_add(&bar[XB_TOPGEN], 1u);
;             else XB_SPIN(xb_ld(&bar[XB_TOPGEN]) == tg, bar);
;             __builtin_amdgcn_fence(__ATOMIC_ACQUIRE, "agent");
;             xb_add(&bar[XB_XGEN(b.x)], 1u);
;             asm volatile("s_waitcnt vmcnt(0)" ::: "memory");
;         } else {
;             XB_SPIN(xb_ld(&bar[XB_XGEN(b.x)]) == gen, bar);
.LBB0_298:
	s_or_b64 exec, exec, s[12:13]
	v_cvt_f32_u32_e32 v4, v2
	s_waitcnt vmcnt(0)
	v_readfirstlane_b32 s4, v3
	v_sub_u32_e32 v3, 0, v2
	v_rcp_iflag_f32_e32 v4, v4
	v_add_u32_e32 v5, s4, v1
	v_mul_f32_e32 v4, 0x4f7ffffe, v4
	v_cvt_u32_f32_e32 v4, v4
	v_mul_lo_u32 v1, v3, v4
	v_mul_hi_u32 v1, v4, v1
	v_add_u32_e32 v1, v4, v1
	v_mul_hi_u32 v1, v5, v1
	v_mul_lo_u32 v3, v1, v2
	v_sub_u32_e32 v3, v5, v3
	v_add_u32_e32 v4, 1, v1
	v_cmp_ge_u32_e32 vcc, v3, v2
	s_nop 1
	v_cndmask_b32_e32 v1, v1, v4, vcc
	v_sub_u32_e32 v4, v3, v2
	v_cndmask_b32_e32 v3, v3, v4, vcc
	v_add_u32_e32 v4, 1, v1
	v_cmp_ge_u32_e32 vcc, v3, v2
	v_add_u32_e32 v3, 1, v5
	s_nop 0
	v_cndmask_b32_e32 v1, v1, v4, vcc
	v_mul_lo_u32 v4, v2, v1
	v_add_u32_e32 v2, v4, v2
	v_cmp_ne_u32_e32 vcc, v3, v2
	s_and_saveexec_b64 s[4:5], vcc
	s_xor_b64 s[12:13], exec, s[4:5]
	s_cbranch_execz .LBB0_312
	buffer_inv sc1
	v_readlane_b32 s4, v255, 4
	s_waitcnt lgkmcnt(0)
	v_mov_b32_e32 v0, 0
	v_readlane_b32 s5, v255, 5
	s_nop 4
	global_load_dword v2, v0, s[4:5] sc1
	s_waitcnt vmcnt(0)
	v_cmp_eq_u32_e32 vcc, v2, v1
	s_and_saveexec_b64 s[28:29], vcc
	s_cbranch_execz .LBB0_311
	s_mov_b32 s4, 1
	s_mov_b64 s[30:31], 0
	s_branch .LBB0_302

; __device__ __forceinline__ unsigned xb_ld(unsigned* p)              { return __hip_atomic_load(p, __ATOMIC_RELAXED, __HIP_MEMORY_SCOPE_AGENT); }
; __device__ __forceinline__ unsigned xb_add(unsigned* p, unsigned v) { return __hip_atomic_fetch_add(p, v, __ATOMIC_RELAXED, __HIP_MEMORY_SCOPE_AGENT); }
; #define XB_SPIN(cond, bar) do { unsigned _sp = 0; while (cond) { __builtin_amdgcn_s_sleep(1); \
;     if ((++_sp & 255u) == 0u) { if (xb_ld(&(bar)[XB_TMO])) break; if (_sp > XB_SPIN_CAP) { atomicAdd(&(bar)[XB_TMO], 1u); break; } } } } while (0)
; __device__ __forceinline__ void xcd_barrier(const XcdBarrier& b) {
;     ...
;             __builtin_amdgcn_fence(__ATOMIC_RELEASE, "agent");
;             asm volatile("s_waitcnt vmcnt(0)" ::: "memory");
;             const unsigned og = xb_add(&bar[XB_TOP], 1u);
;             const unsigned tg = og / nx;
;             if (og + 1u == (tg + 1u) * nx) xb_add(&bar[XB_TOPGEN], 1u);
;             else XB_SPIN(xb_ld(&bar[XB_TOPGEN]) == tg, bar);
;             __builtin_amdgcn_fence(__ATOMIC_ACQUIRE, "agent");
;             xb_add(&bar[XB_XGEN(b.x)], 1u);
;             asm volatile("s_waitcnt vmcnt(0)" ::: "memory");
;         } else {
;             XB_SPIN(xb_ld(&bar[XB_XGEN(b.x)]) == gen, bar);
;             __builtin_amdgcn_fence(__ATOMIC_ACQUIRE, "agent");
;             asm volatile("s_waitcnt vmcnt(0)" ::: "memory");
.LBB0_311:
	s_or_b64 exec, exec, s[28:29]
	s_waitcnt vmcnt(0)
	s_waitcnt vmcnt(0)
.LBB0_312:
	s_andn2_saveexec_b64 s[4:5], s[12:13]
	s_cbranch_execz .LBB0_332
	s_mov_b64 s[12:13], exec
	buffer_wbl2 sc1
	buffer_inv sc1
	s_waitcnt lgkmcnt(0)
	s_waitcnt vmcnt(0)
	v_mbcnt_lo_u32_b32 v1, s12, 0
	v_mbcnt_hi_u32_b32 v1, s13, v1
	v_cmp_eq_u32_e32 vcc, 0, v1
	s_and_saveexec_b64 s[28:29], vcc
	s_cbranch_execz .LBB0_315
	s_bcnt1_i32_b64 s4, s[12:13]
	v_mov_b32_e32 v3, s4
	v_readlane_b32 s4, v255, 6
	v_mov_b32_e32 v2, 0
	v_readlane_b32 s5, v255, 7
	s_nop 4
	global_atomic_add v2, v2, v3, s[4:5] sc0

; __device__ __forceinline__ unsigned xb_ld(unsigned* p)              { return __hip_atomic_load(p, __ATOMIC_RELAXED, __HIP_MEMORY_SCOPE_AGENT); }
; __device__ __forceinline__ unsigned xb_add(unsigned* p, unsigned v) { return __hip_atomic_fetch_add(p, v, __ATOMIC_RELAXED, __HIP_MEMORY_SCOPE_AGENT); }
; #define XB_SPIN(cond, bar) do { unsigned _sp = 0; while (cond) { __builtin_amdgcn_s_sleep(1); \
;     if ((++_sp & 255u) == 0u) { if (xb_ld(&(bar)[XB_TMO])) break; if (_sp > XB_SPIN_CAP) { atomicAdd(&(bar)[XB_TMO], 1u); break; } } } } while (0)
; __device__ __forceinline__ void xcd_barrier(const XcdBarrier& b) {
;     ...
;             else XB_SPIN(xb_ld(&bar[XB_TOPGEN]) == tg, bar);
;             __builtin_amdgcn_fence(__ATOMIC_ACQUIRE, "agent");
;             xb_add(&bar[XB_XGEN(b.x)], 1u);
.LBB0_329:
	s_or_b64 exec, exec, s[12:13]
	s_mov_b64 s[12:13], exec
	v_mbcnt_lo_u32_b32 v0, s12, 0
	v_mbcnt_hi_u32_b32 v0, s13, v0
	v_cmp_eq_u32_e32 vcc, 0, v0
	s_waitcnt vmcnt(0)
	s_and_saveexec_b64 s[28:29], vcc
	s_cbranch_execz .LBB0_331
	s_bcnt1_i32_b64 s4, s[12:13]
	v_mov_b32_e32 v1, s4
	v_readlane_b32 s4, v255, 4
	v_mov_b32_e32 v0, 0
	v_readlane_b32 s5, v255, 5
	s_nop 4
	global_atomic_add v0, v1, s[4:5]

; __device__ __forceinline__ unsigned xb_ld(unsigned* p)              { return __hip_atomic_load(p, __ATOMIC_RELAXED, __HIP_MEMORY_SCOPE_AGENT); }
; __device__ __forceinline__ unsigned xb_add(unsigned* p, unsigned v) { return __hip_atomic_fetch_add(p, v, __ATOMIC_RELAXED, __HIP_MEMORY_SCOPE_AGENT); }
; #define XB_SPIN(cond, bar) do { unsigned _sp = 0; while (cond) { __builtin_amdgcn_s_sleep(1); \
;     if ((++_sp & 255u) == 0u) { if (xb_ld(&(bar)[XB_TMO])) break; if (_sp > XB_SPIN_CAP) { atomicAdd(&(bar)[XB_TMO], 1u); break; } } } } while (0)
; __device__ __forceinline__ void xcd_barrier(const XcdBarrier& b) {
;     ...
;         const unsigned old = xb_add(&bar[XB_XSUB(b.x)], 1u);
;         const unsigned gen = old / nloc;
;         if (old + 1u == (gen + 1u) * nloc) {
;             __builtin_amdgcn_fence(__ATOMIC_RELEASE, "agent");
;             asm volatile("s_waitcnt vmcnt(0)" ::: "memory");
;             const unsigned og = xb_add(&bar[XB_TOP], 1u);
;             const unsigned tg = og / nx;
;             if (og + 1u == (tg + 1u) * nx) xb_add(&bar[XB_TOPGEN], 1u);
;             else XB_SPIN(xb_ld(&bar[XB_TOPGEN]) == tg, bar);
;             __builtin_amdgcn_fence(__ATOMIC_ACQUIRE, "agent");
;             xb_add(&bar[XB_XGEN(b.x)], 1u);
;             asm volatile("s_waitcnt vmcnt(0)" ::: "memory");
;         } else {
;             XB_SPIN(xb_ld(&bar[XB_XGEN(b.x)]) == gen, bar);
.LBB0_427:
	s_or_b64 exec, exec, s[28:29]
	v_cvt_f32_u32_e32 v4, v2
	s_waitcnt vmcnt(0)
	v_readfirstlane_b32 s4, v3
	v_sub_u32_e32 v3, 0, v2
	v_rcp_iflag_f32_e32 v4, v4
	v_add_u32_e32 v5, s4, v1
	v_mul_f32_e32 v4, 0x4f7ffffe, v4
	v_cvt_u32_f32_e32 v4, v4
	v_mul_lo_u32 v1, v3, v4
	v_mul_hi_u32 v1, v4, v1
	v_add_u32_e32 v1, v4, v1
	v_mul_hi_u32 v1, v5, v1
	v_mul_lo_u32 v3, v1, v2
	v_sub_u32_e32 v3, v5, v3
	v_add_u32_e32 v4, 1, v1
	v_cmp_ge_u32_e32 vcc, v3, v2
	s_nop 1
	v_cndmask_b32_e32 v1, v1, v4, vcc
	v_sub_u32_e32 v4, v3, v2
	v_cndmask_b32_e32 v3, v3, v4, vcc
	v_add_u32_e32 v4, 1, v1
	v_cmp_ge_u32_e32 vcc, v3, v2
	v_add_u32_e32 v3, 1, v5
	s_nop 0
	v_cndmask_b32_e32 v1, v1, v4, vcc
	v_mul_lo_u32 v4, v2, v1
	v_add_u32_e32 v2, v4, v2
	v_cmp_ne_u32_e32 vcc, v3, v2
	s_and_saveexec_b64 s[4:5], vcc
	s_xor_b64 s[28:29], exec, s[4:5]
	s_cbranch_execz .LBB0_441
	buffer_inv sc1
	v_readlane_b32 s4, v255, 4
	s_waitcnt lgkmcnt(0)
	v_mov_b32_e32 v0, 0
	v_readlane_b32 s5, v255, 5
	s_nop 4
	global_load_dword v2, v0, s[4:5] sc1
	s_waitcnt vmcnt(0)
	v_cmp_eq_u32_e32 vcc, v2, v1
	s_and_saveexec_b64 s[30:31], vcc
	s_cbranch_execz .LBB0_440
	s_mov_b32 s4, 1
	s_mov_b64 s[34:35], 0
	s_branch .LBB0_431

; __device__ __forceinline__ unsigned xb_ld(unsigned* p)              { return __hip_atomic_load(p, __ATOMIC_RELAXED, __HIP_MEMORY_SCOPE_AGENT); }
; __device__ __forceinline__ unsigned xb_add(unsigned* p, unsigned v) { return __hip_atomic_fetch_add(p, v, __ATOMIC_RELAXED, __HIP_MEMORY_SCOPE_AGENT); }
; #define XB_SPIN(cond, bar) do { unsigned _sp = 0; while (cond) { __builtin_amdgcn_s_sleep(1); \
;     if ((++_sp & 255u) == 0u) { if (xb_ld(&(bar)[XB_TMO])) break; if (_sp > XB_SPIN_CAP) { atomicAdd(&(bar)[XB_TMO], 1u); break; } } } } while (0)
; __device__ __forceinline__ void xcd_barrier(const XcdBarrier& b) {
;     ...
;             __builtin_amdgcn_fence(__ATOMIC_RELEASE, "agent");
;             asm volatile("s_waitcnt vmcnt(0)" ::: "memory");
;             const unsigned og = xb_add(&bar[XB_TOP], 1u);
;             const unsigned tg = og / nx;
;             if (og + 1u == (tg + 1u) * nx) xb_add(&bar[XB_TOPGEN], 1u);
;             else XB_SPIN(xb_ld(&bar[XB_TOPGEN]) == tg, bar);
;             __builtin_amdgcn_fence(__ATOMIC_ACQUIRE, "agent");
;             xb_add(&bar[XB_XGEN(b.x)], 1u);
;             asm volatile("s_waitcnt vmcnt(0)" ::: "memory");
;         } else {
;             XB_SPIN(xb_ld(&bar[XB_XGEN(b.x)]) == gen, bar);
;             __builtin_amdgcn_fence(__ATOMIC_ACQUIRE, "agent");
;             asm volatile("s_waitcnt vmcnt(0)" ::: "memory");
.LBB0_440:
	s_or_b64 exec, exec, s[30:31]
	s_waitcnt vmcnt(0)
	s_waitcnt vmcnt(0)
.LBB0_441:
	s_andn2_saveexec_b64 s[4:5], s[28:29]
	s_cbranch_execz .LBB0_461
	s_mov_b64 s[28:29], exec
	buffer_wbl2 sc1
	buffer_inv sc1
	s_waitcnt lgkmcnt(0)
	s_waitcnt vmcnt(0)
	v_mbcnt_lo_u32_b32 v1, s28, 0
	v_mbcnt_hi_u32_b32 v1, s29, v1
	v_cmp_eq_u32_e32 vcc, 0, v1
	s_and_saveexec_b64 s[30:31], vcc
	s_cbranch_execz .LBB0_444
	s_bcnt1_i32_b64 s4, s[28:29]
	v_mov_b32_e32 v3, s4
	v_readlane_b32 s4, v255, 6
	v_mov_b32_e32 v2, 0
	v_readlane_b32 s5, v255, 7
	s_nop 4
	global_atomic_add v2, v2, v3, s[4:5] sc0

; __device__ __forceinline__ unsigned xb_ld(unsigned* p)              { return __hip_atomic_load(p, __ATOMIC_RELAXED, __HIP_MEMORY_SCOPE_AGENT); }
; __device__ __forceinline__ unsigned xb_add(unsigned* p, unsigned v) { return __hip_atomic_fetch_add(p, v, __ATOMIC_RELAXED, __HIP_MEMORY_SCOPE_AGENT); }
; #define XB_SPIN(cond, bar) do { unsigned _sp = 0; while (cond) { __builtin_amdgcn_s_sleep(1); \
;     if ((++_sp & 255u) == 0u) { if (xb_ld(&(bar)[XB_TMO])) break; if (_sp > XB_SPIN_CAP) { atomicAdd(&(bar)[XB_TMO], 1u); break; } } } } while (0)
; __device__ __forceinline__ void xcd_barrier(const XcdBarrier& b) {
;     ...
;             else XB_SPIN(xb_ld(&bar[XB_TOPGEN]) == tg, bar);
;             __builtin_amdgcn_fence(__ATOMIC_ACQUIRE, "agent");
;             xb_add(&bar[XB_XGEN(b.x)], 1u);
.LBB0_458:
	s_or_b64 exec, exec, s[28:29]
	s_mov_b64 s[28:29], exec
	v_mbcnt_lo_u32_b32 v0, s28, 0
	v_mbcnt_hi_u32_b32 v0, s29, v0
	v_cmp_eq_u32_e32 vcc, 0, v0
	s_waitcnt vmcnt(0)
	s_and_saveexec_b64 s[30:31], vcc
	s_cbranch_execz .LBB0_460
	s_bcnt1_i32_b64 s4, s[28:29]
	v_mov_b32_e32 v1, s4
	v_readlane_b32 s4, v255, 4
	v_mov_b32_e32 v0, 0
	v_readlane_b32 s5, v255, 5
	s_nop 4
	global_atomic_add v0, v1, s[4:5]

; __device__ __forceinline__ unsigned xb_ld(unsigned* p)              { return __hip_atomic_load(p, __ATOMIC_RELAXED, __HIP_MEMORY_SCOPE_AGENT); }
; __device__ __forceinline__ unsigned xb_add(unsigned* p, unsigned v) { return __hip_atomic_fetch_add(p, v, __ATOMIC_RELAXED, __HIP_MEMORY_SCOPE_AGENT); }
; #define XB_SPIN(cond, bar) do { unsigned _sp = 0; while (cond) { __builtin_amdgcn_s_sleep(1); \
;     if ((++_sp & 255u) == 0u) { if (xb_ld(&(bar)[XB_TMO])) break; if (_sp > XB_SPIN_CAP) { atomicAdd(&(bar)[XB_TMO], 1u); break; } } } } while (0)
; __device__ __forceinline__ void xcd_barrier(const XcdBarrier& b) {
;     ...
;         const unsigned old = xb_add(&bar[XB_XSUB(b.x)], 1u);
;         const unsigned gen = old / nloc;
;         if (old + 1u == (gen + 1u) * nloc) {
;             __builtin_amdgcn_fence(__ATOMIC_RELEASE, "agent");
;             asm volatile("s_waitcnt vmcnt(0)" ::: "memory");
;             const unsigned og = xb_add(&bar[XB_TOP], 1u);
;             const unsigned tg = og / nx;
;             if (og + 1u == (tg + 1u) * nx) xb_add(&bar[XB_TOPGEN], 1u);
;             else XB_SPIN(xb_ld(&bar[XB_TOPGEN]) == tg, bar);
;             __builtin_amdgcn_fence(__ATOMIC_ACQUIRE, "agent");
;             xb_add(&bar[XB_XGEN(b.x)], 1u);
;             asm volatile("s_waitcnt vmcnt(0)" ::: "memory");
;         } else {
;             XB_SPIN(xb_ld(&bar[XB_XGEN(b.x)]) == gen, bar);
.LBB0_947:
	s_or_b64 exec, exec, s[4:5]
	v_cvt_f32_u32_e32 v4, v2
	s_waitcnt vmcnt(0)
	v_readfirstlane_b32 s4, v3
	v_sub_u32_e32 v3, 0, v2
	v_rcp_iflag_f32_e32 v4, v4
	v_add_u32_e32 v5, s4, v1
	v_mul_f32_e32 v4, 0x4f7ffffe, v4
	v_cvt_u32_f32_e32 v4, v4
	v_mul_lo_u32 v1, v3, v4
	v_mul_hi_u32 v1, v4, v1
	v_add_u32_e32 v1, v4, v1
	v_mul_hi_u32 v1, v5, v1
	v_mul_lo_u32 v3, v1, v2
	v_sub_u32_e32 v3, v5, v3
	v_add_u32_e32 v4, 1, v1
	v_cmp_ge_u32_e32 vcc, v3, v2
	s_nop 1
	v_cndmask_b32_e32 v1, v1, v4, vcc
	v_sub_u32_e32 v4, v3, v2
	v_cndmask_b32_e32 v3, v3, v4, vcc
	v_add_u32_e32 v4, 1, v1
	v_cmp_ge_u32_e32 vcc, v3, v2
	v_add_u32_e32 v3, 1, v5
	s_nop 0
	v_cndmask_b32_e32 v1, v1, v4, vcc
	v_mul_lo_u32 v4, v2, v1
	v_add_u32_e32 v2, v4, v2
	v_cmp_ne_u32_e32 vcc, v3, v2
	s_and_saveexec_b64 s[4:5], vcc
	s_xor_b64 s[4:5], exec, s[4:5]
	s_cbranch_execz .LBB0_961
	buffer_inv sc1
	v_readlane_b32 s6, v255, 4
	s_waitcnt lgkmcnt(0)
	v_mov_b32_e32 v0, 0
	v_readlane_b32 s7, v255, 5
	s_nop 4
	global_load_dword v2, v0, s[6:7] sc1
	s_waitcnt vmcnt(0)
	v_cmp_eq_u32_e32 vcc, v2, v1
	s_and_saveexec_b64 s[6:7], vcc
	s_cbranch_execz .LBB0_960
	s_mov_b32 s20, 1
	s_mov_b64 s[8:9], 0
	s_branch .LBB0_951

; __device__ __forceinline__ unsigned xb_ld(unsigned* p)              { return __hip_atomic_load(p, __ATOMIC_RELAXED, __HIP_MEMORY_SCOPE_AGENT); }
; __device__ __forceinline__ unsigned xb_add(unsigned* p, unsigned v) { return __hip_atomic_fetch_add(p, v, __ATOMIC_RELAXED, __HIP_MEMORY_SCOPE_AGENT); }
; #define XB_SPIN(cond, bar) do { unsigned _sp = 0; while (cond) { __builtin_amdgcn_s_sleep(1); \
;     if ((++_sp & 255u) == 0u) { if (xb_ld(&(bar)[XB_TMO])) break; if (_sp > XB_SPIN_CAP) { atomicAdd(&(bar)[XB_TMO], 1u); break; } } } } while (0)
; __device__ __forceinline__ void xcd_barrier(const XcdBarrier& b) {
;     ...
;             __builtin_amdgcn_fence(__ATOMIC_RELEASE, "agent");
;             asm volatile("s_waitcnt vmcnt(0)" ::: "memory");
;             const unsigned og = xb_add(&bar[XB_TOP], 1u);
;             const unsigned tg = og / nx;
;             if (og + 1u == (tg + 1u) * nx) xb_add(&bar[XB_TOPGEN], 1u);
;             else XB_SPIN(xb_ld(&bar[XB_TOPGEN]) == tg, bar);
;             __builtin_amdgcn_fence(__ATOMIC_ACQUIRE, "agent");
;             xb_add(&bar[XB_XGEN(b.x)], 1u);
;             asm volatile("s_waitcnt vmcnt(0)" ::: "memory");
;         } else {
;             XB_SPIN(xb_ld(&bar[XB_XGEN(b.x)]) == gen, bar);
;             __builtin_amdgcn_fence(__ATOMIC_ACQUIRE, "agent");
;             asm volatile("s_waitcnt vmcnt(0)" ::: "memory");
.LBB0_960:
	s_or_b64 exec, exec, s[6:7]
	s_waitcnt vmcnt(0)
	s_waitcnt vmcnt(0)
.LBB0_961:
	s_andn2_saveexec_b64 s[4:5], s[4:5]
	s_cbranch_execz .LBB0_981
	s_mov_b64 s[4:5], exec
	buffer_wbl2 sc1
	buffer_inv sc1
	s_waitcnt lgkmcnt(0)
	s_waitcnt vmcnt(0)
	v_mbcnt_lo_u32_b32 v1, s4, 0
	v_mbcnt_hi_u32_b32 v1, s5, v1
	v_cmp_eq_u32_e32 vcc, 0, v1
	s_and_saveexec_b64 s[6:7], vcc
	s_cbranch_execz .LBB0_964
	s_bcnt1_i32_b64 s4, s[4:5]
	v_mov_b32_e32 v3, s4
	v_readlane_b32 s4, v255, 6
	v_mov_b32_e32 v2, 0
	v_readlane_b32 s5, v255, 7
	s_nop 4
	global_atomic_add v2, v2, v3, s[4:5] sc0

; __device__ __forceinline__ unsigned xb_ld(unsigned* p)              { return __hip_atomic_load(p, __ATOMIC_RELAXED, __HIP_MEMORY_SCOPE_AGENT); }
; __device__ __forceinline__ unsigned xb_add(unsigned* p, unsigned v) { return __hip_atomic_fetch_add(p, v, __ATOMIC_RELAXED, __HIP_MEMORY_SCOPE_AGENT); }
; #define XB_SPIN(cond, bar) do { unsigned _sp = 0; while (cond) { __builtin_amdgcn_s_sleep(1); \
;     if ((++_sp & 255u) == 0u) { if (xb_ld(&(bar)[XB_TMO])) break; if (_sp > XB_SPIN_CAP) { atomicAdd(&(bar)[XB_TMO], 1u); break; } } } } while (0)
; __device__ __forceinline__ void xcd_barrier(const XcdBarrier& b) {
;     ...
;             else XB_SPIN(xb_ld(&bar[XB_TOPGEN]) == tg, bar);
;             __builtin_amdgcn_fence(__ATOMIC_ACQUIRE, "agent");
;             xb_add(&bar[XB_XGEN(b.x)], 1u);
.LBB0_978:
	s_or_b64 exec, exec, s[4:5]
	s_mov_b64 s[4:5], exec
	v_mbcnt_lo_u32_b32 v0, s4, 0
	v_mbcnt_hi_u32_b32 v0, s5, v0
	v_cmp_eq_u32_e32 vcc, 0, v0
	s_waitcnt vmcnt(0)
	s_and_saveexec_b64 s[6:7], vcc
	s_cbranch_execz .LBB0_980
	s_bcnt1_i32_b64 s4, s[4:5]
	v_mov_b32_e32 v1, s4
	v_readlane_b32 s4, v255, 4
	v_mov_b32_e32 v0, 0
	v_readlane_b32 s5, v255, 5
	s_nop 4
	global_atomic_add v0, v1, s[4:5]
